# P2-P3 grid barrier replaced by compress-done counter wait (release/acquire), NSA epilogue loads hoisted
# speedup vs baseline: 1.0811x; 1.0200x over previous
; __device__ __forceinline__ void compress_item(const KP& p, int l, int item, char* smem) {
;     ...
;   __syncthreads();
; __device__ __forceinline__ void phase2(const KP& p, int l, char* smem, int* q, int xcc) {
;   xcd_schedule(q, xcc, 196 * 8, 1, smem, [&](int grp, int) __attribute__((always_inline)) {
;     const int y = grp & 7, k = grp >> 3;
;     if (k < 4) compress_item(p, l, k * 8 + y, smem);
;     else if (k < 132) dsa_item(p, y & 1, 511 - ((k - 4) * 4 + (y >> 1)), smem);
;     else pool_item(p, l, (k - 132) * 8 + y, smem);
;   });
.LBB0_603:
	s_waitcnt vmcnt(0)
	s_barrier
	s_and_saveexec_b64 vcc, s[58:59]
	s_cbranch_execz .Lcs_skip
	buffer_wbl2 sc1
	v_readlane_b32 s2, v252, 35
	v_readlane_b32 s3, v252, 36
	s_waitcnt vmcnt(0)
	s_nop 4
	global_atomic_add v1, v226, s[2:3] offset:2048
.Lcs_skip:
	s_or_b64 exec, exec, vcc

;   __device__ __forceinline__ const float* x() const { return (const float*)(const __attribute__((address_space(1))) float*)kp[0]; }
; __device__ __forceinline__ unsigned xb_ld(unsigned* p)              { return __hip_atomic_load(p, __ATOMIC_RELAXED, __HIP_MEMORY_SCOPE_AGENT); }
; __device__ __forceinline__ unsigned xb_add(unsigned* p, unsigned v) { return __hip_atomic_fetch_add(p, v, __ATOMIC_RELAXED, __HIP_MEMORY_SCOPE_AGENT); }
; #define XB_SPIN(cond, bar) do { unsigned _sp = 0; while (cond) { __builtin_amdgcn_s_sleep(1); \
;     if ((++_sp & 255u) == 0u) { if (xb_ld(&(bar)[XB_TMO])) break; if (_sp > XB_SPIN_CAP) { atomicAdd(&(bar)[XB_TMO], 1u); break; } } } } while (0)
; __device__ __forceinline__ void xcd_barrier(const XcdBarrier& b) {
;   asm volatile("s_waitcnt vmcnt(0)" ::: "memory");
;   __syncthreads();
;   if (threadIdx.x == 0) {
;     unsigned* bar = b.bar;
;     __builtin_amdgcn_s_waitcnt(0);
;     unsigned nloc = b.st[0], nx = b.st[1];
;     if (nloc == 0u) { xcd_barrier_complete(bar, b.x, nloc, nx); b.st[0] = nloc; b.st[1] = nx; }
;     const unsigned old = xb_add(&bar[XB_XSUB(b.x)], 1u);
;     const unsigned gen = old / nloc;
;     if (old + 1u == (gen + 1u) * nloc) {
;       __builtin_amdgcn_fence(__ATOMIC_RELEASE, "agent");
;       asm volatile("s_waitcnt vmcnt(0)" ::: "memory");
;       const unsigned og = xb_add(&bar[XB_TOP], 1u);
;       const unsigned tg = og / nx;
;       if (og + 1u == (tg + 1u) * nx) xb_add(&bar[XB_TOPGEN], 1u);
;       else XB_SPIN(xb_ld(&bar[XB_TOPGEN]) == tg, bar);
;       __builtin_amdgcn_fence(__ATOMIC_ACQUIRE, "agent");
;       xb_add(&bar[XB_XGEN(b.x)], 1u);
;       asm volatile("s_waitcnt vmcnt(0)" ::: "memory");
;     } else {
;       XB_SPIN(xb_ld(&bar[XB_XGEN(b.x)]) == gen, bar);
;       __builtin_amdgcn_fence(__ATOMIC_ACQUIRE, "agent");
;       asm volatile("s_waitcnt vmcnt(0)" ::: "memory");
;     }
;   }
;   __syncthreads();
; }
; __global__ void __launch_bounds__(256, 2) fwd_megakernel(Params p_unused) {
;     ...
;     xcd_barrier(xb);
.LBB0_1531:
	s_waitcnt vmcnt(0)
	s_waitcnt vmcnt(63) expcnt(7) lgkmcnt(15)
	s_barrier
	s_and_saveexec_b64 s[0:1], s[58:59]
	s_xor_b64 s[0:1], exec, s[0:1]
	s_cbranch_execz .LBB0_1580
	s_waitcnt vmcnt(0) expcnt(0) lgkmcnt(0)
	v_readlane_b32 s2, v252, 35
	v_readlane_b32 s3, v252, 36
	s_nop 4
.Lcw_spin:
	global_load_dword v0, v1, s[2:3] offset:2048 sc1
	s_waitcnt vmcnt(0)
	v_readfirstlane_b32 s6, v0
	s_nop 3
	s_cmp_ge_u32 s6, 32
	s_cbranch_scc1 .Lcw_ok
	s_sleep 1
	s_branch .Lcw_spin
.Lcw_ok:
	buffer_inv sc1
	s_waitcnt vmcnt(0)

;   __device__ __forceinline__ half_t* vwT() const { return (half_t*)(ws() + OFF_vwT); }
;   __device__ __forceinline__ half_t* yc() const { return (half_t*)(ws() + OFF_yc); }
; __device__ __forceinline__ float siluf_(float x) { return x / (1.f + __expf(-x)); }
; __device__ __forceinline__ void nsa_item(const KP& p, int b, int g, int tile, char* smem) {
;     ...
;     float lt = st.l;
;     lt += __shfl_xor(lt, 32);
;     const float sc = lt > 0.f ? gate[1] / lt : 0.f;
; #pragma unroll
;     for (int dt = 0; dt < 2; ++dt)
; #pragma unroll
;       for (int r = 0; r < 16; ++r) res[dt][r] += sc * st.o[dt][r];
;   }
;   {
;     const half_t* Kw = ub + C_CKW + g * 64;
;     const half_t* Vw = p.vwT() + (size_t)(b * 2 + g) * 64 * SEQ;
;     auto pre = [&](int blk) __attribute__((always_inline)) {
;       return (int)((blk * 64 <= tj) && (blk * 64 + 63 > tj - 512));
;     };
;     auto vfn = [&](int key, int) __attribute__((always_inline)) { return key <= tj && key > tj - 512; };
;     ds_reset(st);
;     auto fullw = [&](int blk) __attribute__((always_inline)) { return blk * 64 + 63 <= tw0 && blk * 64 > tw0 + 7 - 512; };
;     run_dense<true, true, false>(st, Kw, NU, Vw, SEQ, max(0, t0 - 511) >> 6, (t0 + 31) >> 6, qf, pre, fullw, vfn, 0.f, 0.f,
;                                  nopost, smem, tid);
;     float lt = st.l;
;     lt += __shfl_xor(lt, 32);
;     const float sc = lt > 0.f ? gate[2] / lt : 0.f;
; #pragma unroll
;     for (int dt = 0; dt < 2; ++dt)
; #pragma unroll
;       for (int r = 0; r < 16; ++r) res[dt][r] += sc * st.o[dt][r];
;   }
;   half_t* yrow = p.yc() + (size_t)(b * SEQ + tj) * 512 + head * 64;
; #pragma unroll
;   for (int dt = 0; dt < 2; ++dt)
; #pragma unroll
;     for (int qd = 0; qd < 4; ++qd) {
;       const int d = 32 * dt + 8 * qd + 4 * h;
;       const h4 z = *(const h4*)(urow + C_CZ + head * 64 + d);
;       h4 ov;
; #pragma unroll
;       for (int e = 0; e < 4; ++e) ov[e] = (half_t)(res[dt][4 * qd + e] * siluf_((float)z[e]));
;       *(h4*)(yrow + d) = ov;
;     }
.LBB0_1591:
	v_cvt_f32_f16_sdwa v0, v180 dst_sel:DWORD dst_unused:UNUSED_PAD src0_sel:WORD_1
	v_mul_f32_e32 v0, 0xbfb8aa3b, v0
	v_exp_f32_e32 v188, v0
	s_waitcnt lgkmcnt(0)
	v_pk_add_f32 v[2:3], v[188:189], v[186:187]
	s_nop 0
	v_div_scale_f32 v0, s[2:3], v2, v2, 1.0
	v_rcp_f32_e32 v4, v0
	v_cmp_lt_f32_e64 s[38:39], 0, v3
	ds_bpermute_b32 v187, v204, v191
	v_fma_f32 v5, -v0, v4, 1.0
	v_fmac_f32_e32 v4, v5, v4
	v_div_scale_f32 v5, vcc, 1.0, v2, 1.0
	v_mul_f32_e32 v6, v5, v4
	v_fma_f32 v7, -v0, v6, v5
	v_fmac_f32_e32 v6, v7, v4
	v_fma_f32 v0, -v0, v6, v5
	v_div_fmas_f32 v0, v0, v4, v6
	v_div_fixup_f32 v0, v0, v2, 1.0
	v_div_scale_f32 v2, s[2:3], v3, v3, v0
	v_rcp_f32_e32 v4, v2
	s_nop 0
	v_fma_f32 v5, -v2, v4, 1.0
	v_fmac_f32_e32 v4, v5, v4
	v_div_scale_f32 v5, vcc, v0, v3, v0
	v_mul_f32_e32 v6, v5, v4
	v_fma_f32 v7, -v2, v6, v5
	v_fmac_f32_e32 v6, v7, v4
	v_fma_f32 v2, -v2, v6, v5
	v_div_fmas_f32 v2, v2, v4, v6
	v_div_fixup_f32 v0, v2, v3, v0
	v_cndmask_b32_e64 v2, 0, v0, s[38:39]
	v_cvt_f32_f16_e32 v0, v179
	v_mul_f32_e32 v0, 0xbfb8aa3b, v0
	v_exp_f32_e32 v190, v0
	s_waitcnt lgkmcnt(0)
	v_pk_add_f32 v[4:5], v[190:191], v[186:187]
	s_nop 0
	v_div_scale_f32 v0, s[2:3], v4, v4, 1.0
	v_rcp_f32_e32 v3, v0
	v_cmp_lt_f32_e64 s[38:39], 0, v5
	v_fma_f32 v6, -v0, v3, 1.0
	v_fmac_f32_e32 v3, v6, v3
	v_div_scale_f32 v6, vcc, 1.0, v4, 1.0
	v_mul_f32_e32 v7, v6, v3
	v_fma_f32 v8, -v0, v7, v6
	v_fmac_f32_e32 v7, v8, v3
	v_fma_f32 v0, -v0, v7, v6
	v_div_fmas_f32 v0, v0, v3, v7
	v_div_fixup_f32 v0, v0, v4, 1.0
	v_div_scale_f32 v3, s[2:3], v5, v5, v0
	v_rcp_f32_e32 v4, v3
	s_nop 0
	v_fma_f32 v6, -v3, v4, 1.0
	v_fmac_f32_e32 v4, v6, v4
	v_div_scale_f32 v6, vcc, v0, v5, v0
	v_mul_f32_e32 v7, v6, v4
	v_fma_f32 v8, -v3, v7, v6
	v_fmac_f32_e32 v7, v8, v4
	v_fma_f32 v3, -v3, v7, v6
	v_div_fmas_f32 v3, v3, v4, v7
	v_div_fixup_f32 v0, v3, v5, v0
	v_cndmask_b32_e64 v4, 0, v0, s[38:39]
	v_cvt_f32_f16_e32 v0, v180
	v_mul_f32_e32 v0, 0xbfb8aa3b, v0
	v_exp_f32_e32 v0, v0
	s_nop 0
	v_add_f32_e32 v0, 1.0, v0
	v_div_scale_f32 v3, s[2:3], v0, v0, 1.0
	v_rcp_f32_e32 v5, v3
	s_mov_b64 s[2:3], 0x1400
	v_fma_f32 v6, -v3, v5, 1.0
	v_fmac_f32_e32 v5, v6, v5
	v_div_scale_f32 v6, vcc, 1.0, v0, 1.0
	v_mul_f32_e32 v7, v6, v5
	v_fma_f32 v8, -v3, v7, v6
	v_fmac_f32_e32 v7, v8, v5
	v_add_u32_e32 v8, s93, v181
	v_fma_f32 v3, -v3, v7, v6
	v_ashrrev_i32_e32 v9, 31, v8
	v_div_fmas_f32 v3, v3, v5, v7
	v_lshlrev_b64 v[8:9], 10, v[8:9]
	v_div_fixup_f32 v6, v3, v0, 1.0
	v_lshl_add_u64 v[8:9], s[6:7], 0, v[8:9]
	v_lshlrev_b32_e32 v0, 1, v178
	v_lshl_add_u64 v[8:9], v[8:9], 0, v[0:1]
	v_lshl_add_u64 v[10:11], v[176:177], 0, v[0:1]
	v_lshlrev_b32_e32 v0, 1, v198
	v_lshl_add_u64 v[12:13], v[10:11], 0, v[0:1]
	v_lshl_add_u64 v[10:11], v[12:13], 0, s[2:3]
	s_movk_i32 s2, 0x1000
	v_add_co_u32_e32 v12, vcc, s2, v12
	v_pk_fma_f32 v[14:15], v[6:7], v[48:49], 0 op_sel_hi:[0,1,0]
	s_nop 0
	v_addc_co_u32_e32 v13, vcc, 0, v13, vcc
	global_load_dwordx2 v[12:13], v[12:13], off offset:1024
	global_load_dwordx2 v[114:115], v[10:11], off offset:16
	global_load_dwordx2 v[116:117], v[10:11], off offset:32
	global_load_dwordx2 v[118:119], v[10:11], off offset:48
	global_load_dwordx2 v[120:121], v[10:11], off offset:64
	global_load_dwordx2 v[122:123], v[10:11], off offset:80
	global_load_dwordx2 v[124:125], v[10:11], off offset:96
	global_load_dwordx2 v[126:127], v[10:11], off offset:112
	v_pk_fma_f32 v[14:15], v[80:81], v[2:3], v[14:15] op_sel_hi:[1,0,1]
	v_lshl_add_u64 v[8:9], v[8:9], 0, v[0:1]
	v_pk_fma_f32 v[14:15], v[96:97], v[4:5], v[14:15] op_sel_hi:[1,0,1]
	s_waitcnt vmcnt(7)
	v_cvt_f32_f16_e32 v5, v12
	v_cvt_f32_f16_sdwa v3, v12 dst_sel:DWORD dst_unused:UNUSED_PAD src0_sel:WORD_1
	v_mul_f32_e32 v7, 0xbfb8aa3b, v5
	v_exp_f32_e32 v48, v7
	v_mul_f32_e32 v7, 0xbfb8aa3b, v3
	v_exp_f32_e32 v49, v7
	s_nop 0
	v_pk_add_f32 v[48:49], v[48:49], 1.0 op_sel_hi:[1,0]
	s_nop 0
	v_div_scale_f32 v7, s[2:3], v49, v49, v3
	v_rcp_f32_e32 v12, v7
	s_nop 0
	v_fma_f32 v80, -v7, v12, 1.0
	v_fmac_f32_e32 v12, v80, v12
	v_div_scale_f32 v80, vcc, v3, v49, v3
	v_mul_f32_e32 v81, v80, v12
	v_fma_f32 v96, -v7, v81, v80
	v_fmac_f32_e32 v81, v96, v12
	v_fma_f32 v7, -v7, v81, v80
	v_div_fmas_f32 v7, v7, v12, v81
	v_div_fixup_f32 v49, v7, v49, v3
	v_div_scale_f32 v3, s[2:3], v48, v48, v5
	v_rcp_f32_e32 v7, v3
	s_nop 0
	v_fma_f32 v12, -v3, v7, 1.0
	v_fmac_f32_e32 v7, v12, v7
	v_div_scale_f32 v12, vcc, v5, v48, v5
	v_mul_f32_e32 v80, v12, v7
	v_fma_f32 v81, -v3, v80, v12
	v_fmac_f32_e32 v80, v81, v7
	v_fma_f32 v3, -v3, v80, v12
	v_div_fmas_f32 v3, v3, v7, v80
	v_div_fixup_f32 v48, v3, v48, v5
	v_pk_mul_f32 v[14:15], v[14:15], v[48:49]
	s_nop 0
	v_cvt_pk_f16_f32 v12, v14, v15
	v_pk_fma_f32 v[14:15], v[6:7], v[50:51], 0 op_sel_hi:[0,1,0]
	v_pk_fma_f32 v[14:15], v[82:83], v[2:3], v[14:15] op_sel_hi:[1,0,1]
	v_cvt_f32_f16_sdwa v3, v13 dst_sel:DWORD dst_unused:UNUSED_PAD src0_sel:WORD_1
	v_pk_fma_f32 v[14:15], v[98:99], v[4:5], v[14:15] op_sel_hi:[1,0,1]
	v_cvt_f32_f16_e32 v5, v13
	v_mul_f32_e32 v7, 0xbfb8aa3b, v5
	v_exp_f32_e32 v48, v7
	v_mul_f32_e32 v7, 0xbfb8aa3b, v3
	v_exp_f32_e32 v49, v7
	s_nop 0
	v_pk_add_f32 v[48:49], v[48:49], 1.0 op_sel_hi:[1,0]
	s_nop 0
	v_div_scale_f32 v7, s[2:3], v49, v49, v3
	v_rcp_f32_e32 v13, v7
	s_nop 0
	v_fma_f32 v50, -v7, v13, 1.0
	v_fmac_f32_e32 v13, v50, v13
	v_div_scale_f32 v50, vcc, v3, v49, v3
	v_mul_f32_e32 v51, v50, v13
	v_fma_f32 v80, -v7, v51, v50
	v_fmac_f32_e32 v51, v80, v13
	v_fma_f32 v7, -v7, v51, v50
	v_div_fmas_f32 v7, v7, v13, v51
	v_div_fixup_f32 v49, v7, v49, v3
	v_div_scale_f32 v3, s[2:3], v48, v48, v5
	v_rcp_f32_e32 v7, v3
	s_nop 0
	v_fma_f32 v13, -v3, v7, 1.0
	v_fmac_f32_e32 v7, v13, v7
	v_div_scale_f32 v13, vcc, v5, v48, v5
	v_mul_f32_e32 v50, v13, v7
	v_fma_f32 v51, -v3, v50, v13
	v_fmac_f32_e32 v50, v51, v7
	v_fma_f32 v3, -v3, v50, v13
	v_div_fmas_f32 v3, v3, v7, v50
	v_div_fixup_f32 v48, v3, v48, v5
	v_pk_mul_f32 v[14:15], v[14:15], v[48:49]
	s_nop 0
	v_cvt_pk_f16_f32 v13, v14, v15
	global_store_dwordx2 v[8:9], v[12:13], off
	v_pk_fma_f32 v[14:15], v[6:7], v[52:53], 0 op_sel_hi:[0,1,0]
	v_pk_fma_f32 v[14:15], v[84:85], v[2:3], v[14:15] op_sel_hi:[1,0,1]
	s_waitcnt vmcnt(7)
;   __device__ __forceinline__ half_t* yc() const { return (half_t*)(ws() + OFF_yc); }
; __device__ __forceinline__ float siluf_(float x) { return x / (1.f + __expf(-x)); }
; __device__ __forceinline__ void nsa_item(const KP& p, int b, int g, int tile, char* smem) {
;     ...
;     float lt = st.l;
;     lt += __shfl_xor(lt, 32);
;     const float sc = lt > 0.f ? gate[2] / lt : 0.f;
; #pragma unroll
;     for (int dt = 0; dt < 2; ++dt)
; #pragma unroll
;       for (int r = 0; r < 16; ++r) res[dt][r] += sc * st.o[dt][r];
;   }
;   half_t* yrow = p.yc() + (size_t)(b * SEQ + tj) * 512 + head * 64;
; #pragma unroll
;   for (int dt = 0; dt < 2; ++dt)
; #pragma unroll
;     for (int qd = 0; qd < 4; ++qd) {
;       const int d = 32 * dt + 8 * qd + 4 * h;
;       const h4 z = *(const h4*)(urow + C_CZ + head * 64 + d);
;       h4 ov;
; #pragma unroll
;       for (int e = 0; e < 4; ++e) ov[e] = (half_t)(res[dt][4 * qd + e] * siluf_((float)z[e]));
;       *(h4*)(yrow + d) = ov;
;     }
	v_mov_b32_e32 v12, v114
	v_mov_b32_e32 v13, v115
	v_cvt_f32_f16_e32 v3, v12
	v_cvt_f32_f16_sdwa v0, v12 dst_sel:DWORD dst_unused:UNUSED_PAD src0_sel:WORD_1
	v_pk_fma_f32 v[14:15], v[100:101], v[4:5], v[14:15] op_sel_hi:[1,0,1]
	v_mul_f32_e32 v5, 0xbfb8aa3b, v3
	v_exp_f32_e32 v48, v5
	v_mul_f32_e32 v5, 0xbfb8aa3b, v0
	v_exp_f32_e32 v49, v5
	s_nop 0
	v_pk_add_f32 v[48:49], v[48:49], 1.0 op_sel_hi:[1,0]
	s_nop 0
	v_div_scale_f32 v5, s[2:3], v49, v49, v0
	v_rcp_f32_e32 v7, v5
	s_nop 0
	v_fma_f32 v12, -v5, v7, 1.0
	v_fmac_f32_e32 v7, v12, v7
	v_div_scale_f32 v12, vcc, v0, v49, v0
	v_mul_f32_e32 v50, v12, v7
	v_fma_f32 v51, -v5, v50, v12
	v_fmac_f32_e32 v50, v51, v7
	v_fma_f32 v5, -v5, v50, v12
	v_div_fmas_f32 v5, v5, v7, v50
	v_div_fixup_f32 v49, v5, v49, v0
	v_div_scale_f32 v0, s[2:3], v48, v48, v3
	v_rcp_f32_e32 v5, v0
	s_nop 0
	v_fma_f32 v7, -v0, v5, 1.0
	v_fmac_f32_e32 v5, v7, v5
	v_div_scale_f32 v7, vcc, v3, v48, v3
	v_mul_f32_e32 v12, v7, v5
	v_fma_f32 v50, -v0, v12, v7
	v_fmac_f32_e32 v12, v50, v5
	v_fma_f32 v0, -v0, v12, v7
	v_div_fmas_f32 v0, v0, v5, v12
	v_div_fixup_f32 v48, v0, v48, v3
	v_pk_mul_f32 v[14:15], v[14:15], v[48:49]
	v_cvt_f32_f16_sdwa v0, v13 dst_sel:DWORD dst_unused:UNUSED_PAD src0_sel:WORD_1
	v_cvt_pk_f16_f32 v12, v14, v15
	v_pk_fma_f32 v[14:15], v[6:7], v[54:55], 0 op_sel_hi:[0,1,0]
	v_pk_fma_f32 v[14:15], v[86:87], v[2:3], v[14:15] op_sel_hi:[1,0,1]
	v_cvt_f32_f16_e32 v3, v13
	v_pk_fma_f32 v[14:15], v[102:103], v[4:5], v[14:15] op_sel_hi:[1,0,1]
	v_mul_f32_e32 v5, 0xbfb8aa3b, v3
	v_exp_f32_e32 v48, v5
	v_mul_f32_e32 v5, 0xbfb8aa3b, v0
	v_exp_f32_e32 v49, v5
	s_nop 0
	v_pk_add_f32 v[48:49], v[48:49], 1.0 op_sel_hi:[1,0]
	s_nop 0
	v_div_scale_f32 v5, s[2:3], v49, v49, v0
	v_rcp_f32_e32 v7, v5
	s_nop 0
	v_fma_f32 v13, -v5, v7, 1.0
	v_fmac_f32_e32 v7, v13, v7
	v_div_scale_f32 v13, vcc, v0, v49, v0
	v_mul_f32_e32 v50, v13, v7
	v_fma_f32 v51, -v5, v50, v13
	v_fmac_f32_e32 v50, v51, v7
	v_fma_f32 v5, -v5, v50, v13
	v_div_fmas_f32 v5, v5, v7, v50
	v_div_fixup_f32 v49, v5, v49, v0
	v_div_scale_f32 v0, s[2:3], v48, v48, v3
	v_rcp_f32_e32 v5, v0
	s_nop 0
	v_fma_f32 v7, -v0, v5, 1.0
	v_fmac_f32_e32 v5, v7, v5
	v_div_scale_f32 v7, vcc, v3, v48, v3
	v_mul_f32_e32 v13, v7, v5
	v_fma_f32 v50, -v0, v13, v7
	v_fmac_f32_e32 v13, v50, v5
	v_fma_f32 v0, -v0, v13, v7
	v_div_fmas_f32 v0, v0, v5, v13
	v_div_fixup_f32 v48, v0, v48, v3
	v_pk_mul_f32 v[14:15], v[14:15], v[48:49]
	s_nop 0
	v_cvt_pk_f16_f32 v13, v14, v15
	global_store_dwordx2 v[8:9], v[12:13], off offset:16
	v_pk_fma_f32 v[14:15], v[6:7], v[56:57], 0 op_sel_hi:[0,1,0]
	v_pk_fma_f32 v[14:15], v[88:89], v[2:3], v[14:15] op_sel_hi:[1,0,1]
	s_waitcnt vmcnt(7)
	v_mov_b32_e32 v12, v116
	v_mov_b32_e32 v13, v117
	v_cvt_f32_f16_e32 v3, v12
	v_cvt_f32_f16_sdwa v0, v12 dst_sel:DWORD dst_unused:UNUSED_PAD src0_sel:WORD_1
	v_pk_fma_f32 v[14:15], v[104:105], v[4:5], v[14:15] op_sel_hi:[1,0,1]
	v_mul_f32_e32 v5, 0xbfb8aa3b, v3
	v_exp_f32_e32 v48, v5
	v_mul_f32_e32 v5, 0xbfb8aa3b, v0
	v_exp_f32_e32 v49, v5
	s_nop 0
	v_pk_add_f32 v[48:49], v[48:49], 1.0 op_sel_hi:[1,0]
	s_nop 0
	v_div_scale_f32 v5, s[2:3], v49, v49, v0
	v_rcp_f32_e32 v7, v5
	s_nop 0
	v_fma_f32 v12, -v5, v7, 1.0
	v_fmac_f32_e32 v7, v12, v7
	v_div_scale_f32 v12, vcc, v0, v49, v0
	v_mul_f32_e32 v50, v12, v7
	v_fma_f32 v51, -v5, v50, v12
	v_fmac_f32_e32 v50, v51, v7
	v_fma_f32 v5, -v5, v50, v12
	v_div_fmas_f32 v5, v5, v7, v50
	v_div_fixup_f32 v49, v5, v49, v0
	v_div_scale_f32 v0, s[2:3], v48, v48, v3
	v_rcp_f32_e32 v5, v0
	s_nop 0
	v_fma_f32 v7, -v0, v5, 1.0
	v_fmac_f32_e32 v5, v7, v5
	v_div_scale_f32 v7, vcc, v3, v48, v3
	v_mul_f32_e32 v12, v7, v5
	v_fma_f32 v50, -v0, v12, v7
	v_fmac_f32_e32 v12, v50, v5
	v_fma_f32 v0, -v0, v12, v7
	v_div_fmas_f32 v0, v0, v5, v12
	v_div_fixup_f32 v48, v0, v48, v3
	v_pk_mul_f32 v[14:15], v[14:15], v[48:49]
	v_cvt_f32_f16_sdwa v0, v13 dst_sel:DWORD dst_unused:UNUSED_PAD src0_sel:WORD_1
	v_cvt_pk_f16_f32 v12, v14, v15
	v_pk_fma_f32 v[14:15], v[6:7], v[58:59], 0 op_sel_hi:[0,1,0]
	v_pk_fma_f32 v[14:15], v[90:91], v[2:3], v[14:15] op_sel_hi:[1,0,1]
	v_cvt_f32_f16_e32 v3, v13
	v_pk_fma_f32 v[14:15], v[106:107], v[4:5], v[14:15] op_sel_hi:[1,0,1]
	v_mul_f32_e32 v5, 0xbfb8aa3b, v3
	v_exp_f32_e32 v48, v5
	v_mul_f32_e32 v5, 0xbfb8aa3b, v0
	v_exp_f32_e32 v49, v5
	s_nop 0
	v_pk_add_f32 v[48:49], v[48:49], 1.0 op_sel_hi:[1,0]
	s_nop 0
	v_div_scale_f32 v5, s[2:3], v49, v49, v0
	v_rcp_f32_e32 v7, v5
	s_nop 0
	v_fma_f32 v13, -v5, v7, 1.0
	v_fmac_f32_e32 v7, v13, v7
	v_div_scale_f32 v13, vcc, v0, v49, v0
	v_mul_f32_e32 v50, v13, v7
	v_fma_f32 v51, -v5, v50, v13
	v_fmac_f32_e32 v50, v51, v7
	v_fma_f32 v5, -v5, v50, v13
	v_div_fmas_f32 v5, v5, v7, v50
	v_div_fixup_f32 v49, v5, v49, v0
	v_div_scale_f32 v0, s[2:3], v48, v48, v3
	v_rcp_f32_e32 v5, v0
	s_nop 0
	v_fma_f32 v7, -v0, v5, 1.0
	v_fmac_f32_e32 v5, v7, v5
	v_div_scale_f32 v7, vcc, v3, v48, v3
	v_mul_f32_e32 v13, v7, v5
	v_fma_f32 v50, -v0, v13, v7
	v_fmac_f32_e32 v13, v50, v5
	v_fma_f32 v0, -v0, v13, v7
	v_div_fmas_f32 v0, v0, v5, v13
	v_div_fixup_f32 v48, v0, v48, v3
	v_pk_mul_f32 v[14:15], v[14:15], v[48:49]
	s_nop 0
	v_cvt_pk_f16_f32 v13, v14, v15
	global_store_dwordx2 v[8:9], v[12:13], off offset:32
	v_pk_fma_f32 v[14:15], v[6:7], v[60:61], 0 op_sel_hi:[0,1,0]
	v_pk_fma_f32 v[14:15], v[92:93], v[2:3], v[14:15] op_sel_hi:[1,0,1]
	s_waitcnt vmcnt(7)
;   __device__ __forceinline__ half_t* yc() const { return (half_t*)(ws() + OFF_yc); }
; __device__ __forceinline__ float siluf_(float x) { return x / (1.f + __expf(-x)); }
; __device__ __forceinline__ void nsa_item(const KP& p, int b, int g, int tile, char* smem) {
;     ...
;     float lt = st.l;
;     lt += __shfl_xor(lt, 32);
;     const float sc = lt > 0.f ? gate[2] / lt : 0.f;
; #pragma unroll
;     for (int dt = 0; dt < 2; ++dt)
; #pragma unroll
;       for (int r = 0; r < 16; ++r) res[dt][r] += sc * st.o[dt][r];
;   }
;   half_t* yrow = p.yc() + (size_t)(b * SEQ + tj) * 512 + head * 64;
; #pragma unroll
;   for (int dt = 0; dt < 2; ++dt)
; #pragma unroll
;     for (int qd = 0; qd < 4; ++qd) {
;       const int d = 32 * dt + 8 * qd + 4 * h;
;       const h4 z = *(const h4*)(urow + C_CZ + head * 64 + d);
;       h4 ov;
; #pragma unroll
;       for (int e = 0; e < 4; ++e) ov[e] = (half_t)(res[dt][4 * qd + e] * siluf_((float)z[e]));
;       *(h4*)(yrow + d) = ov;
;     }
	v_mov_b32_e32 v12, v118
	v_mov_b32_e32 v13, v119
	v_cvt_f32_f16_e32 v3, v12
	v_cvt_f32_f16_sdwa v0, v12 dst_sel:DWORD dst_unused:UNUSED_PAD src0_sel:WORD_1
	v_pk_fma_f32 v[14:15], v[108:109], v[4:5], v[14:15] op_sel_hi:[1,0,1]
	v_mul_f32_e32 v5, 0xbfb8aa3b, v3
	v_exp_f32_e32 v48, v5
	v_mul_f32_e32 v5, 0xbfb8aa3b, v0
	v_exp_f32_e32 v49, v5
	s_nop 0
	v_pk_add_f32 v[48:49], v[48:49], 1.0 op_sel_hi:[1,0]
	s_nop 0
	v_div_scale_f32 v5, s[2:3], v49, v49, v0
	v_rcp_f32_e32 v7, v5
	s_nop 0
	v_fma_f32 v12, -v5, v7, 1.0
	v_fmac_f32_e32 v7, v12, v7
	v_div_scale_f32 v12, vcc, v0, v49, v0
	v_mul_f32_e32 v50, v12, v7
	v_fma_f32 v51, -v5, v50, v12
	v_fmac_f32_e32 v50, v51, v7
	v_fma_f32 v5, -v5, v50, v12
	v_div_fmas_f32 v5, v5, v7, v50
	v_div_fixup_f32 v49, v5, v49, v0
	v_div_scale_f32 v0, s[2:3], v48, v48, v3
	v_rcp_f32_e32 v5, v0
	s_nop 0
	v_fma_f32 v7, -v0, v5, 1.0
	v_fmac_f32_e32 v5, v7, v5
	v_div_scale_f32 v7, vcc, v3, v48, v3
	v_mul_f32_e32 v12, v7, v5
	v_fma_f32 v50, -v0, v12, v7
	v_fmac_f32_e32 v12, v50, v5
	v_fma_f32 v0, -v0, v12, v7
	v_div_fmas_f32 v0, v0, v5, v12
	v_div_fixup_f32 v48, v0, v48, v3
	v_pk_mul_f32 v[14:15], v[14:15], v[48:49]
	v_cvt_f32_f16_sdwa v0, v13 dst_sel:DWORD dst_unused:UNUSED_PAD src0_sel:WORD_1
	v_cvt_pk_f16_f32 v12, v14, v15
	v_pk_fma_f32 v[14:15], v[6:7], v[62:63], 0 op_sel_hi:[0,1,0]
	v_pk_fma_f32 v[14:15], v[94:95], v[2:3], v[14:15] op_sel_hi:[1,0,1]
	v_cvt_f32_f16_e32 v3, v13
	v_pk_fma_f32 v[14:15], v[110:111], v[4:5], v[14:15] op_sel_hi:[1,0,1]
	v_mul_f32_e32 v5, 0xbfb8aa3b, v3
	v_exp_f32_e32 v48, v5
	v_mul_f32_e32 v5, 0xbfb8aa3b, v0
	v_exp_f32_e32 v49, v5
	s_nop 0
	v_pk_add_f32 v[48:49], v[48:49], 1.0 op_sel_hi:[1,0]
	s_nop 0
	v_div_scale_f32 v5, s[2:3], v49, v49, v0
	v_rcp_f32_e32 v7, v5
	s_nop 0
	v_fma_f32 v13, -v5, v7, 1.0
	v_fmac_f32_e32 v7, v13, v7
	v_div_scale_f32 v13, vcc, v0, v49, v0
	v_mul_f32_e32 v50, v13, v7
	v_fma_f32 v51, -v5, v50, v13
	v_fmac_f32_e32 v50, v51, v7
	v_fma_f32 v5, -v5, v50, v13
	v_div_fmas_f32 v5, v5, v7, v50
	v_div_fixup_f32 v49, v5, v49, v0
	v_div_scale_f32 v0, s[2:3], v48, v48, v3
	v_rcp_f32_e32 v5, v0
	s_nop 0
	v_fma_f32 v7, -v0, v5, 1.0
	v_fmac_f32_e32 v5, v7, v5
	v_div_scale_f32 v7, vcc, v3, v48, v3
	v_mul_f32_e32 v13, v7, v5
	v_fma_f32 v50, -v0, v13, v7
	v_fmac_f32_e32 v13, v50, v5
	v_fma_f32 v0, -v0, v13, v7
	v_div_fmas_f32 v0, v0, v5, v13
	v_div_fixup_f32 v48, v0, v48, v3
	v_pk_mul_f32 v[14:15], v[14:15], v[48:49]
	s_nop 0
	v_cvt_pk_f16_f32 v13, v14, v15
	global_store_dwordx2 v[8:9], v[12:13], off offset:48
	v_pk_fma_f32 v[14:15], v[6:7], v[16:17], 0 op_sel_hi:[0,1,0]
	v_pk_fma_f32 v[14:15], v[32:33], v[2:3], v[14:15] op_sel_hi:[1,0,1]
	s_waitcnt vmcnt(7)
	v_mov_b32_e32 v12, v120
	v_mov_b32_e32 v13, v121
	v_cvt_f32_f16_e32 v3, v12
	v_cvt_f32_f16_sdwa v0, v12 dst_sel:DWORD dst_unused:UNUSED_PAD src0_sel:WORD_1
	v_pk_fma_f32 v[14:15], v[64:65], v[4:5], v[14:15] op_sel_hi:[1,0,1]
	v_mul_f32_e32 v5, 0xbfb8aa3b, v3
	v_exp_f32_e32 v16, v5
	v_mul_f32_e32 v5, 0xbfb8aa3b, v0
	v_exp_f32_e32 v17, v5
	s_nop 0
	v_pk_add_f32 v[16:17], v[16:17], 1.0 op_sel_hi:[1,0]
	s_nop 0
	v_div_scale_f32 v5, s[2:3], v17, v17, v0
	v_rcp_f32_e32 v7, v5
	s_nop 0
	v_fma_f32 v12, -v5, v7, 1.0
	v_fmac_f32_e32 v7, v12, v7
	v_div_scale_f32 v12, vcc, v0, v17, v0
	v_mul_f32_e32 v32, v12, v7
	v_fma_f32 v33, -v5, v32, v12
	v_fmac_f32_e32 v32, v33, v7
	v_fma_f32 v5, -v5, v32, v12
	v_div_fmas_f32 v5, v5, v7, v32
	v_div_fixup_f32 v17, v5, v17, v0
	v_div_scale_f32 v0, s[2:3], v16, v16, v3
	v_rcp_f32_e32 v5, v0
	s_nop 0
	v_fma_f32 v7, -v0, v5, 1.0
	v_fmac_f32_e32 v5, v7, v5
	v_div_scale_f32 v7, vcc, v3, v16, v3
	v_mul_f32_e32 v12, v7, v5
	v_fma_f32 v32, -v0, v12, v7
	v_fmac_f32_e32 v12, v32, v5
	v_fma_f32 v0, -v0, v12, v7
	v_div_fmas_f32 v0, v0, v5, v12
	v_div_fixup_f32 v16, v0, v16, v3
	v_pk_mul_f32 v[14:15], v[14:15], v[16:17]
	v_cvt_f32_f16_sdwa v0, v13 dst_sel:DWORD dst_unused:UNUSED_PAD src0_sel:WORD_1
	v_cvt_pk_f16_f32 v12, v14, v15
	v_pk_fma_f32 v[14:15], v[6:7], v[18:19], 0 op_sel_hi:[0,1,0]
	v_pk_fma_f32 v[14:15], v[34:35], v[2:3], v[14:15] op_sel_hi:[1,0,1]
	v_cvt_f32_f16_e32 v3, v13
	v_pk_fma_f32 v[14:15], v[66:67], v[4:5], v[14:15] op_sel_hi:[1,0,1]
	v_mul_f32_e32 v5, 0xbfb8aa3b, v3
	v_exp_f32_e32 v16, v5
	v_mul_f32_e32 v5, 0xbfb8aa3b, v0
	v_exp_f32_e32 v17, v5
	s_nop 0
	v_pk_add_f32 v[16:17], v[16:17], 1.0 op_sel_hi:[1,0]
	s_nop 0
	v_div_scale_f32 v5, s[2:3], v17, v17, v0
	v_rcp_f32_e32 v7, v5
	s_nop 0
	v_fma_f32 v13, -v5, v7, 1.0
	v_fmac_f32_e32 v7, v13, v7
	v_div_scale_f32 v13, vcc, v0, v17, v0
	v_mul_f32_e32 v18, v13, v7
	v_fma_f32 v19, -v5, v18, v13
	v_fmac_f32_e32 v18, v19, v7
	v_fma_f32 v5, -v5, v18, v13
	v_div_fmas_f32 v5, v5, v7, v18
	v_div_fixup_f32 v17, v5, v17, v0
	v_div_scale_f32 v0, s[2:3], v16, v16, v3
	v_rcp_f32_e32 v5, v0
	s_nop 0
	v_fma_f32 v7, -v0, v5, 1.0
	v_fmac_f32_e32 v5, v7, v5
	v_div_scale_f32 v7, vcc, v3, v16, v3
	v_mul_f32_e32 v13, v7, v5
	v_fma_f32 v18, -v0, v13, v7
	v_fmac_f32_e32 v13, v18, v5
	v_fma_f32 v0, -v0, v13, v7
	v_div_fmas_f32 v0, v0, v5, v13
	v_div_fixup_f32 v16, v0, v16, v3
	v_pk_mul_f32 v[14:15], v[14:15], v[16:17]
	s_nop 0
	v_cvt_pk_f16_f32 v13, v14, v15
	global_store_dwordx2 v[8:9], v[12:13], off offset:64
	v_pk_fma_f32 v[14:15], v[6:7], v[20:21], 0 op_sel_hi:[0,1,0]
	v_pk_fma_f32 v[14:15], v[36:37], v[2:3], v[14:15] op_sel_hi:[1,0,1]
	s_waitcnt vmcnt(7)
;   __device__ __forceinline__ half_t* yc() const { return (half_t*)(ws() + OFF_yc); }
; __device__ __forceinline__ float siluf_(float x) { return x / (1.f + __expf(-x)); }
; __device__ __forceinline__ void nsa_item(const KP& p, int b, int g, int tile, char* smem) {
;     ...
;     float lt = st.l;
;     lt += __shfl_xor(lt, 32);
;     const float sc = lt > 0.f ? gate[2] / lt : 0.f;
; #pragma unroll
;     for (int dt = 0; dt < 2; ++dt)
; #pragma unroll
;       for (int r = 0; r < 16; ++r) res[dt][r] += sc * st.o[dt][r];
;   }
;   half_t* yrow = p.yc() + (size_t)(b * SEQ + tj) * 512 + head * 64;
; #pragma unroll
;   for (int dt = 0; dt < 2; ++dt)
; #pragma unroll
;     for (int qd = 0; qd < 4; ++qd) {
;       const int d = 32 * dt + 8 * qd + 4 * h;
;       const h4 z = *(const h4*)(urow + C_CZ + head * 64 + d);
;       h4 ov;
; #pragma unroll
;       for (int e = 0; e < 4; ++e) ov[e] = (half_t)(res[dt][4 * qd + e] * siluf_((float)z[e]));
;       *(h4*)(yrow + d) = ov;
;     }
	v_mov_b32_e32 v12, v122
	v_mov_b32_e32 v13, v123
	v_cvt_f32_f16_e32 v3, v12
	v_cvt_f32_f16_sdwa v0, v12 dst_sel:DWORD dst_unused:UNUSED_PAD src0_sel:WORD_1
	v_pk_fma_f32 v[14:15], v[68:69], v[4:5], v[14:15] op_sel_hi:[1,0,1]
	v_mul_f32_e32 v5, 0xbfb8aa3b, v3
	v_exp_f32_e32 v16, v5
	v_mul_f32_e32 v5, 0xbfb8aa3b, v0
	v_exp_f32_e32 v17, v5
	s_nop 0
	v_pk_add_f32 v[16:17], v[16:17], 1.0 op_sel_hi:[1,0]
	s_nop 0
	v_div_scale_f32 v5, s[2:3], v17, v17, v0
	v_rcp_f32_e32 v7, v5
	s_nop 0
	v_fma_f32 v12, -v5, v7, 1.0
	v_fmac_f32_e32 v7, v12, v7
	v_div_scale_f32 v12, vcc, v0, v17, v0
	v_mul_f32_e32 v18, v12, v7
	v_fma_f32 v19, -v5, v18, v12
	v_fmac_f32_e32 v18, v19, v7
	v_fma_f32 v5, -v5, v18, v12
	v_div_fmas_f32 v5, v5, v7, v18
	v_div_fixup_f32 v17, v5, v17, v0
	v_div_scale_f32 v0, s[2:3], v16, v16, v3
	v_rcp_f32_e32 v5, v0
	s_nop 0
	v_fma_f32 v7, -v0, v5, 1.0
	v_fmac_f32_e32 v5, v7, v5
	v_div_scale_f32 v7, vcc, v3, v16, v3
	v_mul_f32_e32 v12, v7, v5
	v_fma_f32 v18, -v0, v12, v7
	v_fmac_f32_e32 v12, v18, v5
	v_fma_f32 v0, -v0, v12, v7
	v_div_fmas_f32 v0, v0, v5, v12
	v_div_fixup_f32 v16, v0, v16, v3
	v_pk_mul_f32 v[14:15], v[14:15], v[16:17]
	v_cvt_f32_f16_sdwa v0, v13 dst_sel:DWORD dst_unused:UNUSED_PAD src0_sel:WORD_1
	v_cvt_pk_f16_f32 v12, v14, v15
	v_pk_fma_f32 v[14:15], v[6:7], v[22:23], 0 op_sel_hi:[0,1,0]
	v_pk_fma_f32 v[14:15], v[38:39], v[2:3], v[14:15] op_sel_hi:[1,0,1]
	v_cvt_f32_f16_e32 v3, v13
	v_pk_fma_f32 v[14:15], v[70:71], v[4:5], v[14:15] op_sel_hi:[1,0,1]
	v_mul_f32_e32 v5, 0xbfb8aa3b, v3
	v_exp_f32_e32 v16, v5
	v_mul_f32_e32 v5, 0xbfb8aa3b, v0
	v_exp_f32_e32 v17, v5
	s_nop 0
	v_pk_add_f32 v[16:17], v[16:17], 1.0 op_sel_hi:[1,0]
	s_nop 0
	v_div_scale_f32 v5, s[2:3], v17, v17, v0
	v_rcp_f32_e32 v7, v5
	s_nop 0
	v_fma_f32 v13, -v5, v7, 1.0
	v_fmac_f32_e32 v7, v13, v7
	v_div_scale_f32 v13, vcc, v0, v17, v0
	v_mul_f32_e32 v18, v13, v7
	v_fma_f32 v19, -v5, v18, v13
	v_fmac_f32_e32 v18, v19, v7
	v_fma_f32 v5, -v5, v18, v13
	v_div_fmas_f32 v5, v5, v7, v18
	v_div_fixup_f32 v17, v5, v17, v0
	v_div_scale_f32 v0, s[2:3], v16, v16, v3
	v_rcp_f32_e32 v5, v0
	s_nop 0
	v_fma_f32 v7, -v0, v5, 1.0
	v_fmac_f32_e32 v5, v7, v5
	v_div_scale_f32 v7, vcc, v3, v16, v3
	v_mul_f32_e32 v13, v7, v5
	v_fma_f32 v18, -v0, v13, v7
	v_fmac_f32_e32 v13, v18, v5
	v_fma_f32 v0, -v0, v13, v7
	v_div_fmas_f32 v0, v0, v5, v13
	v_div_fixup_f32 v16, v0, v16, v3
	v_pk_mul_f32 v[14:15], v[14:15], v[16:17]
	s_nop 0
	v_cvt_pk_f16_f32 v13, v14, v15
	global_store_dwordx2 v[8:9], v[12:13], off offset:80
	v_pk_fma_f32 v[14:15], v[6:7], v[24:25], 0 op_sel_hi:[0,1,0]
	v_pk_fma_f32 v[14:15], v[40:41], v[2:3], v[14:15] op_sel_hi:[1,0,1]
	s_waitcnt vmcnt(7)
	v_mov_b32_e32 v12, v124
	v_mov_b32_e32 v13, v125
	v_cvt_f32_f16_e32 v3, v12
	v_cvt_f32_f16_sdwa v0, v12 dst_sel:DWORD dst_unused:UNUSED_PAD src0_sel:WORD_1
	v_pk_fma_f32 v[14:15], v[72:73], v[4:5], v[14:15] op_sel_hi:[1,0,1]
	v_mul_f32_e32 v5, 0xbfb8aa3b, v3
	v_exp_f32_e32 v16, v5
	v_mul_f32_e32 v5, 0xbfb8aa3b, v0
	v_exp_f32_e32 v17, v5
	s_nop 0
	v_pk_add_f32 v[16:17], v[16:17], 1.0 op_sel_hi:[1,0]
	s_nop 0
	v_div_scale_f32 v5, s[2:3], v17, v17, v0
	v_rcp_f32_e32 v7, v5
	s_nop 0
	v_fma_f32 v12, -v5, v7, 1.0
	v_fmac_f32_e32 v7, v12, v7
	v_div_scale_f32 v12, vcc, v0, v17, v0
	v_mul_f32_e32 v18, v12, v7
	v_fma_f32 v19, -v5, v18, v12
	v_fmac_f32_e32 v18, v19, v7
	v_fma_f32 v5, -v5, v18, v12
	v_div_fmas_f32 v5, v5, v7, v18
	v_div_fixup_f32 v17, v5, v17, v0
	v_div_scale_f32 v0, s[2:3], v16, v16, v3
	v_rcp_f32_e32 v5, v0
	s_nop 0
	v_fma_f32 v7, -v0, v5, 1.0
	v_fmac_f32_e32 v5, v7, v5
	v_div_scale_f32 v7, vcc, v3, v16, v3
	v_mul_f32_e32 v12, v7, v5
	v_fma_f32 v18, -v0, v12, v7
	v_fmac_f32_e32 v12, v18, v5
	v_fma_f32 v0, -v0, v12, v7
	v_div_fmas_f32 v0, v0, v5, v12
	v_div_fixup_f32 v16, v0, v16, v3
	v_pk_mul_f32 v[14:15], v[14:15], v[16:17]
	v_cvt_f32_f16_sdwa v0, v13 dst_sel:DWORD dst_unused:UNUSED_PAD src0_sel:WORD_1
	v_cvt_pk_f16_f32 v12, v14, v15
	v_pk_fma_f32 v[14:15], v[6:7], v[26:27], 0 op_sel_hi:[0,1,0]
	v_pk_fma_f32 v[14:15], v[42:43], v[2:3], v[14:15] op_sel_hi:[1,0,1]
	v_cvt_f32_f16_e32 v3, v13
	v_pk_fma_f32 v[14:15], v[74:75], v[4:5], v[14:15] op_sel_hi:[1,0,1]
	v_mul_f32_e32 v5, 0xbfb8aa3b, v3
	v_exp_f32_e32 v16, v5
	v_mul_f32_e32 v5, 0xbfb8aa3b, v0
	v_exp_f32_e32 v17, v5
	s_nop 0
	v_pk_add_f32 v[16:17], v[16:17], 1.0 op_sel_hi:[1,0]
	s_nop 0
	v_div_scale_f32 v5, s[2:3], v17, v17, v0
	v_rcp_f32_e32 v7, v5
	s_nop 0
	v_fma_f32 v13, -v5, v7, 1.0
	v_fmac_f32_e32 v7, v13, v7
	v_div_scale_f32 v13, vcc, v0, v17, v0
	v_mul_f32_e32 v18, v13, v7
	v_fma_f32 v19, -v5, v18, v13
	v_fmac_f32_e32 v18, v19, v7
	v_fma_f32 v5, -v5, v18, v13
	v_div_fmas_f32 v5, v5, v7, v18
	v_div_fixup_f32 v17, v5, v17, v0
	v_div_scale_f32 v0, s[2:3], v16, v16, v3
	v_rcp_f32_e32 v5, v0
	s_nop 0
	v_fma_f32 v7, -v0, v5, 1.0
	v_fmac_f32_e32 v5, v7, v5
	v_div_scale_f32 v7, vcc, v3, v16, v3
	v_mul_f32_e32 v13, v7, v5
	v_fma_f32 v18, -v0, v13, v7
	v_fmac_f32_e32 v13, v18, v5
	v_fma_f32 v0, -v0, v13, v7
	v_div_fmas_f32 v0, v0, v5, v13
	v_div_fixup_f32 v16, v0, v16, v3
	v_pk_mul_f32 v[14:15], v[14:15], v[16:17]
	s_waitcnt vmcnt(6)
;   __device__ __forceinline__ half_t* yc() const { return (half_t*)(ws() + OFF_yc); }
; __device__ __forceinline__ float siluf_(float x) { return x / (1.f + __expf(-x)); }
; __device__ __forceinline__ void nsa_item(const KP& p, int b, int g, int tile, char* smem) {
;     ...
;     float lt = st.l;
;     lt += __shfl_xor(lt, 32);
;     const float sc = lt > 0.f ? gate[2] / lt : 0.f;
; #pragma unroll
;     for (int dt = 0; dt < 2; ++dt)
; #pragma unroll
;       for (int r = 0; r < 16; ++r) res[dt][r] += sc * st.o[dt][r];
;   }
;   half_t* yrow = p.yc() + (size_t)(b * SEQ + tj) * 512 + head * 64;
; #pragma unroll
;   for (int dt = 0; dt < 2; ++dt)
; #pragma unroll
;     for (int qd = 0; qd < 4; ++qd) {
;       const int d = 32 * dt + 8 * qd + 4 * h;
;       const h4 z = *(const h4*)(urow + C_CZ + head * 64 + d);
;       h4 ov;
; #pragma unroll
;       for (int e = 0; e < 4; ++e) ov[e] = (half_t)(res[dt][4 * qd + e] * siluf_((float)z[e]));
;       *(h4*)(yrow + d) = ov;
;     }
	v_mov_b32_e32 v10, v126
	v_mov_b32_e32 v11, v127
	v_cvt_f32_f16_sdwa v0, v10 dst_sel:DWORD dst_unused:UNUSED_PAD src0_sel:WORD_1
	v_cvt_pk_f16_f32 v13, v14, v15
	global_store_dwordx2 v[8:9], v[12:13], off offset:96
	v_pk_fma_f32 v[12:13], v[6:7], v[28:29], 0 op_sel_hi:[0,1,0]
	v_pk_fma_f32 v[12:13], v[44:45], v[2:3], v[12:13] op_sel_hi:[1,0,1]
	v_cvt_f32_f16_e32 v3, v10
	v_pk_fma_f32 v[12:13], v[76:77], v[4:5], v[12:13] op_sel_hi:[1,0,1]
	v_mul_f32_e32 v5, 0xbfb8aa3b, v3
	v_exp_f32_e32 v14, v5
	v_mul_f32_e32 v5, 0xbfb8aa3b, v0
	v_exp_f32_e32 v15, v5
	s_nop 0
	v_pk_add_f32 v[14:15], v[14:15], 1.0 op_sel_hi:[1,0]
	s_nop 0
	v_div_scale_f32 v5, s[2:3], v15, v15, v0
	v_rcp_f32_e32 v7, v5
	s_nop 0
	v_fma_f32 v10, -v5, v7, 1.0
	v_fmac_f32_e32 v7, v10, v7
	v_div_scale_f32 v10, vcc, v0, v15, v0
	v_mul_f32_e32 v16, v10, v7
	v_fma_f32 v17, -v5, v16, v10
	v_fmac_f32_e32 v16, v17, v7
	v_fma_f32 v5, -v5, v16, v10
	v_div_fmas_f32 v5, v5, v7, v16
	v_div_fixup_f32 v15, v5, v15, v0
	v_div_scale_f32 v0, s[2:3], v14, v14, v3
	v_rcp_f32_e32 v5, v0
	s_nop 0
	v_fma_f32 v7, -v0, v5, 1.0
	v_fmac_f32_e32 v5, v7, v5
	v_div_scale_f32 v7, vcc, v3, v14, v3
	v_mul_f32_e32 v10, v7, v5
	v_fma_f32 v16, -v0, v10, v7
	v_fmac_f32_e32 v10, v16, v5
	v_fma_f32 v0, -v0, v10, v7
	v_div_fmas_f32 v0, v0, v5, v10
	v_pk_fma_f32 v[6:7], v[6:7], v[30:31], 0 op_sel_hi:[0,1,0]
	v_div_fixup_f32 v14, v0, v14, v3
	v_pk_fma_f32 v[2:3], v[46:47], v[2:3], v[6:7] op_sel_hi:[1,0,1]
	v_cvt_f32_f16_sdwa v0, v11 dst_sel:DWORD dst_unused:UNUSED_PAD src0_sel:WORD_1
	v_cvt_f32_f16_e32 v6, v11
	v_pk_fma_f32 v[2:3], v[78:79], v[4:5], v[2:3] op_sel_hi:[1,0,1]
	v_pk_mul_f32 v[12:13], v[12:13], v[14:15]
	v_mul_f32_e32 v5, 0xbfb8aa3b, v0
	v_mul_f32_e32 v4, 0xbfb8aa3b, v6
	v_exp_f32_e32 v4, v4
	v_exp_f32_e32 v5, v5
	v_cvt_pk_f16_f32 v10, v12, v13
	v_pk_add_f32 v[4:5], v[4:5], 1.0 op_sel_hi:[1,0]
	s_nop 0
	v_div_scale_f32 v7, s[2:3], v5, v5, v0
	v_rcp_f32_e32 v11, v7
	s_nop 0
	v_fma_f32 v12, -v7, v11, 1.0
	v_fmac_f32_e32 v11, v12, v11
	v_div_scale_f32 v12, vcc, v0, v5, v0
	v_mul_f32_e32 v13, v12, v11
	v_fma_f32 v14, -v7, v13, v12
	v_fmac_f32_e32 v13, v14, v11
	v_fma_f32 v7, -v7, v13, v12
	v_div_fmas_f32 v7, v7, v11, v13
	v_div_fixup_f32 v5, v7, v5, v0
	v_div_scale_f32 v0, s[2:3], v4, v4, v6
	v_rcp_f32_e32 v7, v0
	s_nop 0
	v_fma_f32 v11, -v0, v7, 1.0
	v_fmac_f32_e32 v7, v11, v7
	v_div_scale_f32 v11, vcc, v6, v4, v6
	v_mul_f32_e32 v12, v11, v7
	v_fma_f32 v13, -v0, v12, v11
	v_fmac_f32_e32 v12, v13, v7
	v_fma_f32 v0, -v0, v12, v11
	v_div_fmas_f32 v0, v0, v7, v12
	v_div_fixup_f32 v4, v0, v4, v6
	v_pk_mul_f32 v[2:3], v[2:3], v[4:5]
	s_nop 0
	v_cvt_pk_f16_f32 v11, v2, v3
	global_store_dwordx2 v[8:9], v[10:11], off offset:112
	s_barrier
